# v16 + in-proj K loop: the compiler's conservative s_waitcnt vmcnt(0) between the fragment ds_reads removed (the counted vmcnt(8) + barrier protocol already orders the LDS-DMA data, as in the other thr
# speedup vs baseline: 1.0125x; 1.0041x over previous
; #define G_STAGE_B(bufoff, gbase) do { G_GLDS((const char*)(gbase) + voffB0, (bufoff) + ldsw); G_GLDS((const char*)(gbase) + vstep64 + voffB0, (bufoff) + ldsw + 8192); } while (0)
; #define G_STAGE_AU(bufoff, gbase) do { G_GLDS((const char*)(gbase) + voffA0, (bufoff) + ldsw); G_GLDS((const char*)(gbase) + vstep64 + voffA0, (bufoff) + ldsw + 8192); } while (0)
; #define X_LDA(b, h) do { if constexpr (MODE == 2) G_LDA8(A8, b, h); else G_LDA(At, b, h); } while (0)
; #define X_LDB0(b, h) do { if constexpr (MODE == 2) G_LDB8(B08, b, h); else G_LDB(B0, b, h); } while (0)
; #define X_LDB1(b, h) do { if constexpr (MODE == 2) G_LDB8(B18, b, h); else G_LDB(B1, b, h); } while (0)
; #define X_MMA0(ai, bj) do { if constexpr (MODE == 2) G_MMA8(ai, bj, A8, B08); else G_MMA(ai, bj, At, B0); } while (0)
; #define X_MMA1(ai, bj) do { if constexpr (MODE == 2) G_MMA8(ai, bj, A8, B18); else G_MMA(ai, bj, At, B1); } while (0)
; #define G_WAIT_V(n) asm volatile("s_waitcnt vmcnt(" #n ")" ::: "memory")
; #define G_WAIT_L(n) asm volatile("s_waitcnt lgkmcnt(" #n ")" ::: "memory")
; #define G_BAR __builtin_amdgcn_s_barrier()
; #define G_SCHED __builtin_amdgcn_sched_barrier(0)
;     ...
;             X_LDB0(0, 0); X_LDB1(0, 1); G_SCHED; X_LDA(0, 0); G_STAGE_AU(G_SA(1, 1), a1 + hstep);
;             G_WAIT_V(8); G_WAIT_L(0); G_BAR; X_MMA0(0, 0); X_MMA1(0, 1); G_BAR; G_SCHED;
;             X_LDA(0, 1); G_STAGE_B(G_SB(0, 0), b2); G_STAGE_B(G_SB(0, 1), b2 + hstep); G_STAGE_AU(G_SA(0, 0), a2);
;             G_WAIT_V(8); G_WAIT_L(0); G_BAR; X_MMA0(1, 0); X_MMA1(1, 1); G_BAR; G_SCHED;
.Lmy_peel_inproj_203:
	ds_read_b128 v[132:135], v217
	ds_read_b128 v[136:139], v217 offset:1024
	ds_read_b128 v[146:149], v217 offset:2048
	ds_read_b128 v[150:153], v217 offset:3072
	ds_read_b128 v[154:157], v218
	ds_read_b128 v[158:161], v218 offset:1024
	ds_read_b128 v[162:165], v218 offset:2048
	ds_read_b128 v[166:169], v218 offset:3072
	s_add_u32 s16, s0, 0xfffe0080
	s_addc_u32 s38, s1, -1
	s_cmp_eq_u32 s11, 4
	s_cselect_b32 s39, s3, s38
	s_cselect_b32 s38, s6, s16
	s_cselect_b32 s95, s7, s9
	s_cselect_b32 s94, s10, s8
	s_mov_b32 m0, s69
	v_lshl_add_u64 v[202:203], s[0:1], 0, v[144:145]
	ds_read_b128 v[170:173], v219
	ds_read_b128 v[174:177], v219 offset:1024
	ds_read_b128 v[178:181], v219 offset:2048
	ds_read_b128 v[182:185], v219 offset:3072
	ds_read_b128 v[186:189], v219 offset:4096
	ds_read_b128 v[190:193], v219 offset:5120
	ds_read_b128 v[194:197], v219 offset:6144
	ds_read_b128 v[198:201], v219 offset:7168
	global_load_lds_dwordx4 v[202:203], off
	v_lshl_add_u64 v[202:203], v[202:203], 0, s[20:21]
	s_mov_b32 m0, s72
	s_nop 0
	global_load_lds_dwordx4 v[202:203], off
	s_waitcnt vmcnt(8)
	s_waitcnt lgkmcnt(0)
	s_barrier
	s_setprio 1
	s_waitcnt lgkmcnt(0)
	v_mfma_i32_16x16x64_i8 v[128:131], v[132:135], v[170:173], 0
	v_mfma_i32_16x16x64_i8 v[124:127], v[146:149], v[170:173], 0
	v_mfma_i32_16x16x64_i8 v[120:123], v[132:135], v[178:181], 0
	v_mfma_i32_16x16x64_i8 v[116:119], v[146:149], v[178:181], 0
	v_mfma_i32_16x16x64_i8 v[112:115], v[132:135], v[186:189], 0
	v_mfma_i32_16x16x64_i8 v[108:111], v[146:149], v[186:189], 0
	v_mfma_i32_16x16x64_i8 v[104:107], v[132:135], v[194:197], 0
	v_mfma_i32_16x16x64_i8 v[100:103], v[146:149], v[194:197], 0
	v_mfma_i32_16x16x64_i8 v[128:131], v[136:139], v[174:177], v[128:131]
	v_mfma_i32_16x16x64_i8 v[124:127], v[150:153], v[174:177], v[124:127]
	v_mfma_i32_16x16x64_i8 v[120:123], v[136:139], v[182:185], v[120:123]
	v_mfma_i32_16x16x64_i8 v[116:119], v[150:153], v[182:185], v[116:119]
	v_mfma_i32_16x16x64_i8 v[112:115], v[136:139], v[190:193], v[112:115]
	v_mfma_i32_16x16x64_i8 v[108:111], v[150:153], v[190:193], v[108:111]
	v_mfma_i32_16x16x64_i8 v[104:107], v[136:139], v[198:201], v[104:107]
	v_mfma_i32_16x16x64_i8 v[100:103], v[150:153], v[198:201], v[100:103]
	s_setprio 0
	s_setprio 1
	v_mfma_i32_16x16x64_i8 v[62:65], v[154:157], v[170:173], 0
	v_mfma_i32_16x16x64_i8 v[58:61], v[162:165], v[170:173], 0
	v_mfma_i32_16x16x64_i8 v[54:57], v[154:157], v[178:181], 0
	v_mfma_i32_16x16x64_i8 v[50:53], v[162:165], v[178:181], 0
	v_mfma_i32_16x16x64_i8 v[46:49], v[154:157], v[186:189], 0
	v_mfma_i32_16x16x64_i8 v[42:45], v[162:165], v[186:189], 0
	v_mfma_i32_16x16x64_i8 v[38:41], v[154:157], v[194:197], 0
	v_mfma_i32_16x16x64_i8 v[34:37], v[162:165], v[194:197], 0
	v_mfma_i32_16x16x64_i8 v[62:65], v[158:161], v[174:177], v[62:65]
	v_mfma_i32_16x16x64_i8 v[58:61], v[166:169], v[174:177], v[58:61]
	v_mfma_i32_16x16x64_i8 v[54:57], v[158:161], v[182:185], v[54:57]
	v_mfma_i32_16x16x64_i8 v[50:53], v[166:169], v[182:185], v[50:53]
	v_mfma_i32_16x16x64_i8 v[46:49], v[158:161], v[190:193], v[46:49]
	v_mfma_i32_16x16x64_i8 v[42:45], v[166:169], v[190:193], v[42:45]
	v_mfma_i32_16x16x64_i8 v[38:41], v[158:161], v[198:201], v[38:41]
	v_mfma_i32_16x16x64_i8 v[34:37], v[166:169], v[198:201], v[34:37]
	s_setprio 0
	s_barrier
	s_mov_b32 m0, s26
	v_lshl_add_u64 v[202:203], s[94:95], 0, v[142:143]
	ds_read_b128 v[170:173], v219 offset:16384
	ds_read_b128 v[174:177], v219 offset:17408
	ds_read_b128 v[178:181], v219 offset:18432
	ds_read_b128 v[182:185], v219 offset:19456
	ds_read_b128 v[186:189], v219 offset:20480
	ds_read_b128 v[190:193], v219 offset:21504
	ds_read_b128 v[194:197], v219 offset:22528
	ds_read_b128 v[198:201], v219 offset:23552
	global_load_lds_dwordx4 v[202:203], off
	v_lshl_add_u64 v[204:205], v[202:203], 0, s[20:21]
	s_mov_b32 m0, s27
	s_nop 0
	global_load_lds_dwordx4 v[204:205], off
	v_lshl_add_u64 v[204:205], v[202:203], 0, s[18:19]
	s_mov_b32 m0, s28
	s_nop 0
	global_load_lds_dwordx4 v[204:205], off
	v_lshl_add_u64 v[204:205], v[202:203], 0, s[92:93]
	s_mov_b32 m0, s29
	s_nop 0
	global_load_lds_dwordx4 v[204:205], off
	v_lshl_add_u64 v[204:205], s[38:39], 0, v[140:141]
	s_mov_b32 m0, s25
	v_lshl_add_u64 v[206:207], v[204:205], 0, s[20:21]
	global_load_lds_dwordx4 v[204:205], off
	s_mov_b32 m0, s58
	s_nop 0
	global_load_lds_dwordx4 v[206:207], off
	s_waitcnt vmcnt(8)
	s_waitcnt lgkmcnt(0)
	s_barrier
	s_setprio 1
	s_waitcnt lgkmcnt(0)
	v_mfma_i32_16x16x64_i8 v[96:99], v[132:135], v[170:173], 0
	v_mfma_i32_16x16x64_i8 v[92:95], v[146:149], v[170:173], 0
	v_mfma_i32_16x16x64_i8 v[88:91], v[132:135], v[178:181], 0
	v_mfma_i32_16x16x64_i8 v[84:87], v[146:149], v[178:181], 0
	v_mfma_i32_16x16x64_i8 v[80:83], v[132:135], v[186:189], 0
	v_mfma_i32_16x16x64_i8 v[76:79], v[146:149], v[186:189], 0
	v_mfma_i32_16x16x64_i8 v[72:75], v[132:135], v[194:197], 0
	v_mfma_i32_16x16x64_i8 v[68:71], v[146:149], v[194:197], 0
	v_mfma_i32_16x16x64_i8 v[96:99], v[136:139], v[174:177], v[96:99]
	v_mfma_i32_16x16x64_i8 v[92:95], v[150:153], v[174:177], v[92:95]
	v_mfma_i32_16x16x64_i8 v[88:91], v[136:139], v[182:185], v[88:91]
	v_mfma_i32_16x16x64_i8 v[84:87], v[150:153], v[182:185], v[84:87]
	v_mfma_i32_16x16x64_i8 v[80:83], v[136:139], v[190:193], v[80:83]
	v_mfma_i32_16x16x64_i8 v[76:79], v[150:153], v[190:193], v[76:79]
	v_mfma_i32_16x16x64_i8 v[72:75], v[136:139], v[198:201], v[72:75]
	v_mfma_i32_16x16x64_i8 v[68:71], v[150:153], v[198:201], v[68:71]
	s_setprio 0
	s_setprio 1
	v_mfma_i32_16x16x64_i8 v[30:33], v[154:157], v[170:173], 0
	v_mfma_i32_16x16x64_i8 v[26:29], v[162:165], v[170:173], 0
	v_mfma_i32_16x16x64_i8 v[22:25], v[154:157], v[178:181], 0
	v_mfma_i32_16x16x64_i8 v[18:21], v[162:165], v[178:181], 0
	v_mfma_i32_16x16x64_i8 v[14:17], v[154:157], v[186:189], 0
	v_mfma_i32_16x16x64_i8 v[10:13], v[162:165], v[186:189], 0
	v_mfma_i32_16x16x64_i8 v[6:9], v[154:157], v[194:197], 0
	v_mfma_i32_16x16x64_i8 v[2:5], v[162:165], v[194:197], 0
	v_mfma_i32_16x16x64_i8 v[30:33], v[158:161], v[174:177], v[30:33]
	v_mfma_i32_16x16x64_i8 v[26:29], v[166:169], v[174:177], v[26:29]
	v_mfma_i32_16x16x64_i8 v[22:25], v[158:161], v[182:185], v[22:25]
	v_mfma_i32_16x16x64_i8 v[18:21], v[166:169], v[182:185], v[18:21]
	v_mfma_i32_16x16x64_i8 v[14:17], v[158:161], v[190:193], v[14:17]
	v_mfma_i32_16x16x64_i8 v[10:13], v[166:169], v[190:193], v[10:13]
	v_mfma_i32_16x16x64_i8 v[6:9], v[158:161], v[198:201], v[6:9]
	v_mfma_i32_16x16x64_i8 v[2:5], v[166:169], v[198:201], v[2:5]
	s_setprio 0
	s_barrier
; #define G_STAGE_B(bufoff, gbase) do { G_GLDS((const char*)(gbase) + voffB0, (bufoff) + ldsw); G_GLDS((const char*)(gbase) + vstep64 + voffB0, (bufoff) + ldsw + 8192); } while (0)
; #define G_STAGE_AU(bufoff, gbase) do { G_GLDS((const char*)(gbase) + voffA0, (bufoff) + ldsw); G_GLDS((const char*)(gbase) + vstep64 + voffA0, (bufoff) + ldsw + 8192); } while (0)
; #define X_LDA(b, h) do { if constexpr (MODE == 2) G_LDA8(A8, b, h); else G_LDA(At, b, h); } while (0)
; #define X_LDB0(b, h) do { if constexpr (MODE == 2) G_LDB8(B08, b, h); else G_LDB(B0, b, h); } while (0)
; #define X_LDB1(b, h) do { if constexpr (MODE == 2) G_LDB8(B18, b, h); else G_LDB(B1, b, h); } while (0)
; #define X_MMA0(ai, bj) do { if constexpr (MODE == 2) G_MMA8(ai, bj, A8, B08); else G_MMA(ai, bj, At, B0); } while (0)
; #define X_MMA1(ai, bj) do { if constexpr (MODE == 2) G_MMA8(ai, bj, A8, B18); else G_MMA(ai, bj, At, B1); } while (0)
; #define G_WAIT_V(n) asm volatile("s_waitcnt vmcnt(" #n ")" ::: "memory")
; #define G_WAIT_L(n) asm volatile("s_waitcnt lgkmcnt(" #n ")" ::: "memory")
; #define G_BAR __builtin_amdgcn_s_barrier()
; #define G_SCHED __builtin_amdgcn_sched_barrier(0)
;     ...
;             X_LDB0(1, 0); X_LDB1(1, 1); G_SCHED; X_LDA(1, 0); G_STAGE_AU(G_SA(0, 1), a2 + hstep);
;             G_WAIT_V(8); G_WAIT_L(0); G_BAR; X_MMA0(0, 0); X_MMA1(0, 1); G_BAR; G_SCHED;
;             X_LDA(1, 1); G_STAGE_B(G_SB(1, 0), b3); G_STAGE_B(G_SB(1, 1), b3 + hstep); G_STAGE_AU(G_SA(1, 0), a3);
;             G_WAIT_V(8); G_WAIT_L(0); G_BAR; X_MMA0(1, 0); X_MMA1(1, 1); G_BAR; G_SCHED;
	ds_read_b128 v[132:135], v231
	ds_read_b128 v[136:139], v231 offset:1024
	ds_read_b128 v[146:149], v231 offset:2048
	ds_read_b128 v[150:153], v231 offset:3072
	ds_read_b128 v[154:157], v232
	ds_read_b128 v[158:161], v232 offset:1024
	ds_read_b128 v[162:165], v232 offset:2048
	ds_read_b128 v[166:169], v232 offset:3072
	s_mov_b32 m0, s59
	v_lshl_add_u64 v[206:207], v[204:205], 0, s[18:19]
	ds_read_b128 v[170:173], v219 offset:32768
	ds_read_b128 v[174:177], v219 offset:33792
	ds_read_b128 v[178:181], v219 offset:34816
	ds_read_b128 v[182:185], v219 offset:35840
	ds_read_b128 v[186:189], v219 offset:36864
	ds_read_b128 v[190:193], v219 offset:37888
	ds_read_b128 v[194:197], v219 offset:38912
	ds_read_b128 v[198:201], v219 offset:39936
	global_load_lds_dwordx4 v[206:207], off
	v_lshl_add_u64 v[206:207], v[204:205], 0, s[92:93]
	s_mov_b32 m0, s60
	s_nop 0
	global_load_lds_dwordx4 v[206:207], off
	s_waitcnt vmcnt(8)
	s_waitcnt lgkmcnt(0)
	s_barrier
	s_setprio 1
	s_waitcnt lgkmcnt(0)
	v_mfma_i32_16x16x64_i8 v[128:131], v[132:135], v[170:173], v[128:131]
	v_mfma_i32_16x16x64_i8 v[124:127], v[146:149], v[170:173], v[124:127]
	v_mfma_i32_16x16x64_i8 v[120:123], v[132:135], v[178:181], v[120:123]
	v_mfma_i32_16x16x64_i8 v[116:119], v[146:149], v[178:181], v[116:119]
	v_mfma_i32_16x16x64_i8 v[112:115], v[132:135], v[186:189], v[112:115]
	v_mfma_i32_16x16x64_i8 v[108:111], v[146:149], v[186:189], v[108:111]
	v_mfma_i32_16x16x64_i8 v[104:107], v[132:135], v[194:197], v[104:107]
	v_mfma_i32_16x16x64_i8 v[100:103], v[146:149], v[194:197], v[100:103]
	v_mfma_i32_16x16x64_i8 v[128:131], v[136:139], v[174:177], v[128:131]
	v_mfma_i32_16x16x64_i8 v[124:127], v[150:153], v[174:177], v[124:127]
	v_mfma_i32_16x16x64_i8 v[120:123], v[136:139], v[182:185], v[120:123]
	v_mfma_i32_16x16x64_i8 v[116:119], v[150:153], v[182:185], v[116:119]
	v_mfma_i32_16x16x64_i8 v[112:115], v[136:139], v[190:193], v[112:115]
	v_mfma_i32_16x16x64_i8 v[108:111], v[150:153], v[190:193], v[108:111]
	v_mfma_i32_16x16x64_i8 v[104:107], v[136:139], v[198:201], v[104:107]
	v_mfma_i32_16x16x64_i8 v[100:103], v[150:153], v[198:201], v[100:103]
	s_setprio 0
	s_setprio 1
	v_mfma_i32_16x16x64_i8 v[62:65], v[154:157], v[170:173], v[62:65]
	v_mfma_i32_16x16x64_i8 v[58:61], v[162:165], v[170:173], v[58:61]
	v_mfma_i32_16x16x64_i8 v[54:57], v[154:157], v[178:181], v[54:57]
	v_mfma_i32_16x16x64_i8 v[50:53], v[162:165], v[178:181], v[50:53]
	v_mfma_i32_16x16x64_i8 v[46:49], v[154:157], v[186:189], v[46:49]
	v_mfma_i32_16x16x64_i8 v[42:45], v[162:165], v[186:189], v[42:45]
	v_mfma_i32_16x16x64_i8 v[38:41], v[154:157], v[194:197], v[38:41]
	v_mfma_i32_16x16x64_i8 v[34:37], v[162:165], v[194:197], v[34:37]
	v_mfma_i32_16x16x64_i8 v[62:65], v[158:161], v[174:177], v[62:65]
	v_mfma_i32_16x16x64_i8 v[58:61], v[166:169], v[174:177], v[58:61]
	v_mfma_i32_16x16x64_i8 v[54:57], v[158:161], v[182:185], v[54:57]
	v_mfma_i32_16x16x64_i8 v[50:53], v[166:169], v[182:185], v[50:53]
	v_mfma_i32_16x16x64_i8 v[46:49], v[158:161], v[190:193], v[46:49]
	v_mfma_i32_16x16x64_i8 v[42:45], v[166:169], v[190:193], v[42:45]
	v_mfma_i32_16x16x64_i8 v[38:41], v[158:161], v[198:201], v[38:41]
	v_mfma_i32_16x16x64_i8 v[34:37], v[166:169], v[198:201], v[34:37]
	s_setprio 0
	s_barrier
	s_mov_b32 m0, s61
	v_lshl_add_u64 v[206:207], v[202:203], 0, s[82:83]
	ds_read_b128 v[170:173], v219 offset:49152
	ds_read_b128 v[174:177], v219 offset:50176
	ds_read_b128 v[178:181], v219 offset:51200
	ds_read_b128 v[182:185], v219 offset:52224
	ds_read_b128 v[186:189], v219 offset:53248
	ds_read_b128 v[190:193], v219 offset:54272
	ds_read_b128 v[194:197], v219 offset:55296
	ds_read_b128 v[198:201], v219 offset:56320
	global_load_lds_dwordx4 v[206:207], off
	v_lshl_add_u64 v[206:207], v[202:203], 0, s[22:23]
	s_mov_b32 m0, s62
	s_nop 0
	global_load_lds_dwordx4 v[206:207], off
	v_lshl_add_u64 v[206:207], v[202:203], 0, s[88:89]
	s_mov_b32 m0, s65
	v_lshl_add_u64 v[202:203], v[202:203], 0, s[74:75]
	global_load_lds_dwordx4 v[206:207], off
	s_mov_b32 m0, s66
	s_nop 0
	global_load_lds_dwordx4 v[202:203], off
	v_lshl_add_u64 v[202:203], v[204:205], 0, s[82:83]
	s_mov_b32 m0, s63
	s_nop 0
	global_load_lds_dwordx4 v[202:203], off
	v_lshl_add_u64 v[202:203], v[204:205], 0, s[22:23]
	s_mov_b32 m0, s64
	s_nop 0
	global_load_lds_dwordx4 v[202:203], off
	s_waitcnt vmcnt(8)
	s_waitcnt lgkmcnt(0)
	s_barrier
	s_setprio 1
	s_waitcnt lgkmcnt(0)
	v_mfma_i32_16x16x64_i8 v[96:99], v[132:135], v[170:173], v[96:99]
	v_mfma_i32_16x16x64_i8 v[92:95], v[146:149], v[170:173], v[92:95]
	v_mfma_i32_16x16x64_i8 v[88:91], v[132:135], v[178:181], v[88:91]
	v_mfma_i32_16x16x64_i8 v[84:87], v[146:149], v[178:181], v[84:87]
	v_mfma_i32_16x16x64_i8 v[80:83], v[132:135], v[186:189], v[80:83]
	v_mfma_i32_16x16x64_i8 v[76:79], v[146:149], v[186:189], v[76:79]
	v_mfma_i32_16x16x64_i8 v[72:75], v[132:135], v[194:197], v[72:75]
	v_mfma_i32_16x16x64_i8 v[68:71], v[146:149], v[194:197], v[68:71]
	v_mfma_i32_16x16x64_i8 v[96:99], v[136:139], v[174:177], v[96:99]
	v_mfma_i32_16x16x64_i8 v[92:95], v[150:153], v[174:177], v[92:95]
	v_mfma_i32_16x16x64_i8 v[88:91], v[136:139], v[182:185], v[88:91]
	v_mfma_i32_16x16x64_i8 v[84:87], v[150:153], v[182:185], v[84:87]
	v_mfma_i32_16x16x64_i8 v[80:83], v[136:139], v[190:193], v[80:83]
	v_mfma_i32_16x16x64_i8 v[76:79], v[150:153], v[190:193], v[76:79]
	v_mfma_i32_16x16x64_i8 v[72:75], v[136:139], v[198:201], v[72:75]
	v_mfma_i32_16x16x64_i8 v[68:71], v[150:153], v[198:201], v[68:71]
	s_setprio 0
	s_setprio 1
	v_mfma_i32_16x16x64_i8 v[30:33], v[154:157], v[170:173], v[30:33]
	v_mfma_i32_16x16x64_i8 v[26:29], v[162:165], v[170:173], v[26:29]
	v_mfma_i32_16x16x64_i8 v[22:25], v[154:157], v[178:181], v[22:25]
	v_mfma_i32_16x16x64_i8 v[18:21], v[162:165], v[178:181], v[18:21]
	v_mfma_i32_16x16x64_i8 v[14:17], v[154:157], v[186:189], v[14:17]
	v_mfma_i32_16x16x64_i8 v[10:13], v[162:165], v[186:189], v[10:13]
	v_mfma_i32_16x16x64_i8 v[6:9], v[154:157], v[194:197], v[6:9]
	v_mfma_i32_16x16x64_i8 v[2:5], v[162:165], v[194:197], v[2:5]
	v_mfma_i32_16x16x64_i8 v[30:33], v[158:161], v[174:177], v[30:33]
	v_mfma_i32_16x16x64_i8 v[26:29], v[166:169], v[174:177], v[26:29]
	v_mfma_i32_16x16x64_i8 v[22:25], v[158:161], v[182:185], v[22:25]
	v_mfma_i32_16x16x64_i8 v[18:21], v[166:169], v[182:185], v[18:21]
	v_mfma_i32_16x16x64_i8 v[14:17], v[158:161], v[190:193], v[14:17]
	v_mfma_i32_16x16x64_i8 v[10:13], v[166:169], v[190:193], v[10:13]
	v_mfma_i32_16x16x64_i8 v[6:9], v[158:161], v[198:201], v[6:9]
	v_mfma_i32_16x16x64_i8 v[2:5], v[166:169], v[198:201], v[2:5]
	s_setprio 0
	s_barrier
	s_add_i32 s11, s11, 2
	s_add_u32 s0, s0, 0x100
	s_addc_u32 s1, s1, 0
	s_add_u32 s8, s8, 0x100
	s_addc_u32 s9, s9, 0
	s_cmp_gt_u32 s11, 5
	s_cbranch_scc1 .Lmy_peel_inproj_exit
; #define G_STAGE_B(bufoff, gbase) do { G_GLDS((const char*)(gbase) + voffB0, (bufoff) + ldsw); G_GLDS((const char*)(gbase) + vstep64 + voffB0, (bufoff) + ldsw + 8192); } while (0)
; #define G_STAGE_AU(bufoff, gbase) do { G_GLDS((const char*)(gbase) + voffA0, (bufoff) + ldsw); G_GLDS((const char*)(gbase) + vstep64 + voffA0, (bufoff) + ldsw + 8192); } while (0)
; #define X_LDA(b, h) do { if constexpr (MODE == 2) G_LDA8(A8, b, h); else G_LDA(At, b, h); } while (0)
; #define X_LDB0(b, h) do { if constexpr (MODE == 2) G_LDB8(B08, b, h); else G_LDB(B0, b, h); } while (0)
; #define X_LDB1(b, h) do { if constexpr (MODE == 2) G_LDB8(B18, b, h); else G_LDB(B1, b, h); } while (0)
; #define X_MMA0(ai, bj) do { if constexpr (MODE == 2) G_MMA8(ai, bj, A8, B08); else G_MMA(ai, bj, At, B0); } while (0)
; #define X_MMA1(ai, bj) do { if constexpr (MODE == 2) G_MMA8(ai, bj, A8, B18); else G_MMA(ai, bj, At, B1); } while (0)
; #define G_WAIT_V(n) asm volatile("s_waitcnt vmcnt(" #n ")" ::: "memory")
; #define G_WAIT_L(n) asm volatile("s_waitcnt lgkmcnt(" #n ")" ::: "memory")
; #define G_BAR __builtin_amdgcn_s_barrier()
; #define G_SCHED __builtin_amdgcn_sched_barrier(0)
;     ...
;             X_LDB0(0, 0); X_LDB1(0, 1); G_SCHED; X_LDA(0, 0); G_STAGE_AU(G_SA(1, 1), a1 + hstep);
;             G_WAIT_V(8); G_WAIT_L(0); G_BAR; X_MMA0(0, 0); X_MMA1(0, 1); G_BAR; G_SCHED;
;             X_LDA(0, 1); G_STAGE_B(G_SB(0, 0), b2); G_STAGE_B(G_SB(0, 1), b2 + hstep); G_STAGE_AU(G_SA(0, 0), a2);
;             G_WAIT_V(8); G_WAIT_L(0); G_BAR; X_MMA0(1, 0); X_MMA1(1, 1); G_BAR; G_SCHED;
.LBB0_203:
	ds_read_b128 v[132:135], v217
	ds_read_b128 v[136:139], v217 offset:1024
	ds_read_b128 v[146:149], v217 offset:2048
	ds_read_b128 v[150:153], v217 offset:3072
	ds_read_b128 v[154:157], v218
	ds_read_b128 v[158:161], v218 offset:1024
	ds_read_b128 v[162:165], v218 offset:2048
	ds_read_b128 v[166:169], v218 offset:3072
	s_add_u32 s16, s0, 0xfffe0080
	s_addc_u32 s38, s1, -1
	s_cmp_eq_u32 s11, 4
	s_cselect_b32 s39, s3, s38
	s_cselect_b32 s38, s6, s16
	s_cselect_b32 s95, s7, s9
	s_cselect_b32 s94, s10, s8
	s_mov_b32 m0, s69
	v_lshl_add_u64 v[202:203], s[0:1], 0, v[144:145]
	ds_read_b128 v[170:173], v219
	ds_read_b128 v[174:177], v219 offset:1024
	ds_read_b128 v[178:181], v219 offset:2048
	ds_read_b128 v[182:185], v219 offset:3072
	ds_read_b128 v[186:189], v219 offset:4096
	ds_read_b128 v[190:193], v219 offset:5120
	ds_read_b128 v[194:197], v219 offset:6144
	ds_read_b128 v[198:201], v219 offset:7168
	global_load_lds_dwordx4 v[202:203], off
	v_lshl_add_u64 v[202:203], v[202:203], 0, s[20:21]
	s_mov_b32 m0, s72
	s_nop 0
	global_load_lds_dwordx4 v[202:203], off
	s_waitcnt vmcnt(8)
	s_waitcnt lgkmcnt(0)
	s_barrier
	s_setprio 1
	s_waitcnt lgkmcnt(0)
	v_mfma_i32_16x16x64_i8 v[128:131], v[132:135], v[170:173], v[128:131]
	v_mfma_i32_16x16x64_i8 v[124:127], v[146:149], v[170:173], v[124:127]
	v_mfma_i32_16x16x64_i8 v[120:123], v[132:135], v[178:181], v[120:123]
	v_mfma_i32_16x16x64_i8 v[116:119], v[146:149], v[178:181], v[116:119]
	v_mfma_i32_16x16x64_i8 v[112:115], v[132:135], v[186:189], v[112:115]
	v_mfma_i32_16x16x64_i8 v[108:111], v[146:149], v[186:189], v[108:111]
	v_mfma_i32_16x16x64_i8 v[104:107], v[132:135], v[194:197], v[104:107]
	v_mfma_i32_16x16x64_i8 v[100:103], v[146:149], v[194:197], v[100:103]
	v_mfma_i32_16x16x64_i8 v[128:131], v[136:139], v[174:177], v[128:131]
	v_mfma_i32_16x16x64_i8 v[124:127], v[150:153], v[174:177], v[124:127]
	v_mfma_i32_16x16x64_i8 v[120:123], v[136:139], v[182:185], v[120:123]
	v_mfma_i32_16x16x64_i8 v[116:119], v[150:153], v[182:185], v[116:119]
	v_mfma_i32_16x16x64_i8 v[112:115], v[136:139], v[190:193], v[112:115]
	v_mfma_i32_16x16x64_i8 v[108:111], v[150:153], v[190:193], v[108:111]
	v_mfma_i32_16x16x64_i8 v[104:107], v[136:139], v[198:201], v[104:107]
	v_mfma_i32_16x16x64_i8 v[100:103], v[150:153], v[198:201], v[100:103]
	s_setprio 0
	s_setprio 1
	v_mfma_i32_16x16x64_i8 v[62:65], v[154:157], v[170:173], v[62:65]
	v_mfma_i32_16x16x64_i8 v[58:61], v[162:165], v[170:173], v[58:61]
	v_mfma_i32_16x16x64_i8 v[54:57], v[154:157], v[178:181], v[54:57]
	v_mfma_i32_16x16x64_i8 v[50:53], v[162:165], v[178:181], v[50:53]
	v_mfma_i32_16x16x64_i8 v[46:49], v[154:157], v[186:189], v[46:49]
	v_mfma_i32_16x16x64_i8 v[42:45], v[162:165], v[186:189], v[42:45]
	v_mfma_i32_16x16x64_i8 v[38:41], v[154:157], v[194:197], v[38:41]
	v_mfma_i32_16x16x64_i8 v[34:37], v[162:165], v[194:197], v[34:37]
	v_mfma_i32_16x16x64_i8 v[62:65], v[158:161], v[174:177], v[62:65]
	v_mfma_i32_16x16x64_i8 v[58:61], v[166:169], v[174:177], v[58:61]
	v_mfma_i32_16x16x64_i8 v[54:57], v[158:161], v[182:185], v[54:57]
	v_mfma_i32_16x16x64_i8 v[50:53], v[166:169], v[182:185], v[50:53]
	v_mfma_i32_16x16x64_i8 v[46:49], v[158:161], v[190:193], v[46:49]
	v_mfma_i32_16x16x64_i8 v[42:45], v[166:169], v[190:193], v[42:45]
	v_mfma_i32_16x16x64_i8 v[38:41], v[158:161], v[198:201], v[38:41]
	v_mfma_i32_16x16x64_i8 v[34:37], v[166:169], v[198:201], v[34:37]
	s_setprio 0
	s_barrier
	s_mov_b32 m0, s26
	v_lshl_add_u64 v[202:203], s[94:95], 0, v[142:143]
	ds_read_b128 v[170:173], v219 offset:16384
	ds_read_b128 v[174:177], v219 offset:17408
	ds_read_b128 v[178:181], v219 offset:18432
	ds_read_b128 v[182:185], v219 offset:19456
	ds_read_b128 v[186:189], v219 offset:20480
	ds_read_b128 v[190:193], v219 offset:21504
	ds_read_b128 v[194:197], v219 offset:22528
	ds_read_b128 v[198:201], v219 offset:23552
	global_load_lds_dwordx4 v[202:203], off
	v_lshl_add_u64 v[204:205], v[202:203], 0, s[20:21]
	s_mov_b32 m0, s27
	s_nop 0
	global_load_lds_dwordx4 v[204:205], off
	v_lshl_add_u64 v[204:205], v[202:203], 0, s[18:19]
	s_mov_b32 m0, s28
	s_nop 0
	global_load_lds_dwordx4 v[204:205], off
	v_lshl_add_u64 v[204:205], v[202:203], 0, s[92:93]
	s_mov_b32 m0, s29
	s_nop 0
	global_load_lds_dwordx4 v[204:205], off
	v_lshl_add_u64 v[204:205], s[38:39], 0, v[140:141]
	s_mov_b32 m0, s25
	v_lshl_add_u64 v[206:207], v[204:205], 0, s[20:21]
	global_load_lds_dwordx4 v[204:205], off
	s_mov_b32 m0, s58
	s_nop 0
	global_load_lds_dwordx4 v[206:207], off
	s_waitcnt vmcnt(8)
	s_waitcnt lgkmcnt(0)
	s_barrier
; #define G_STAGE_AU(bufoff, gbase) do { G_GLDS((const char*)(gbase) + voffA0, (bufoff) + ldsw); G_GLDS((const char*)(gbase) + vstep64 + voffA0, (bufoff) + ldsw + 8192); } while (0)
; #define X_LDA(b, h) do { if constexpr (MODE == 2) G_LDA8(A8, b, h); else G_LDA(At, b, h); } while (0)
; #define X_LDB0(b, h) do { if constexpr (MODE == 2) G_LDB8(B08, b, h); else G_LDB(B0, b, h); } while (0)
; #define X_LDB1(b, h) do { if constexpr (MODE == 2) G_LDB8(B18, b, h); else G_LDB(B1, b, h); } while (0)
; #define X_MMA0(ai, bj) do { if constexpr (MODE == 2) G_MMA8(ai, bj, A8, B08); else G_MMA(ai, bj, At, B0); } while (0)
; #define X_MMA1(ai, bj) do { if constexpr (MODE == 2) G_MMA8(ai, bj, A8, B18); else G_MMA(ai, bj, At, B1); } while (0)
; #define G_WAIT_V(n) asm volatile("s_waitcnt vmcnt(" #n ")" ::: "memory")
; #define G_WAIT_L(n) asm volatile("s_waitcnt lgkmcnt(" #n ")" ::: "memory")
; #define G_BAR __builtin_amdgcn_s_barrier()
; #define G_SCHED __builtin_amdgcn_sched_barrier(0)
;     ...
;             G_WAIT_V(8); G_WAIT_L(0); G_BAR; X_MMA0(1, 0); X_MMA1(1, 1); G_BAR; G_SCHED;
;             X_LDB0(1, 0); X_LDB1(1, 1); G_SCHED; X_LDA(1, 0); G_STAGE_AU(G_SA(0, 1), a2 + hstep);
;             G_WAIT_V(8); G_WAIT_L(0); G_BAR; X_MMA0(0, 0); X_MMA1(0, 1); G_BAR; G_SCHED;
	s_setprio 1
	s_waitcnt lgkmcnt(0)
	v_mfma_i32_16x16x64_i8 v[96:99], v[132:135], v[170:173], v[96:99]
	v_mfma_i32_16x16x64_i8 v[92:95], v[146:149], v[170:173], v[92:95]
	v_mfma_i32_16x16x64_i8 v[88:91], v[132:135], v[178:181], v[88:91]
	v_mfma_i32_16x16x64_i8 v[84:87], v[146:149], v[178:181], v[84:87]
	v_mfma_i32_16x16x64_i8 v[80:83], v[132:135], v[186:189], v[80:83]
	v_mfma_i32_16x16x64_i8 v[76:79], v[146:149], v[186:189], v[76:79]
	v_mfma_i32_16x16x64_i8 v[72:75], v[132:135], v[194:197], v[72:75]
	v_mfma_i32_16x16x64_i8 v[68:71], v[146:149], v[194:197], v[68:71]
	v_mfma_i32_16x16x64_i8 v[96:99], v[136:139], v[174:177], v[96:99]
	v_mfma_i32_16x16x64_i8 v[92:95], v[150:153], v[174:177], v[92:95]
	v_mfma_i32_16x16x64_i8 v[88:91], v[136:139], v[182:185], v[88:91]
	v_mfma_i32_16x16x64_i8 v[84:87], v[150:153], v[182:185], v[84:87]
	v_mfma_i32_16x16x64_i8 v[80:83], v[136:139], v[190:193], v[80:83]
	v_mfma_i32_16x16x64_i8 v[76:79], v[150:153], v[190:193], v[76:79]
	v_mfma_i32_16x16x64_i8 v[72:75], v[136:139], v[198:201], v[72:75]
	v_mfma_i32_16x16x64_i8 v[68:71], v[150:153], v[198:201], v[68:71]
	s_setprio 0
	s_setprio 1
	v_mfma_i32_16x16x64_i8 v[30:33], v[154:157], v[170:173], v[30:33]
	v_mfma_i32_16x16x64_i8 v[26:29], v[162:165], v[170:173], v[26:29]
	v_mfma_i32_16x16x64_i8 v[22:25], v[154:157], v[178:181], v[22:25]
	v_mfma_i32_16x16x64_i8 v[18:21], v[162:165], v[178:181], v[18:21]
	v_mfma_i32_16x16x64_i8 v[14:17], v[154:157], v[186:189], v[14:17]
	v_mfma_i32_16x16x64_i8 v[10:13], v[162:165], v[186:189], v[10:13]
	v_mfma_i32_16x16x64_i8 v[6:9], v[154:157], v[194:197], v[6:9]
	v_mfma_i32_16x16x64_i8 v[2:5], v[162:165], v[194:197], v[2:5]
	v_mfma_i32_16x16x64_i8 v[30:33], v[158:161], v[174:177], v[30:33]
	v_mfma_i32_16x16x64_i8 v[26:29], v[166:169], v[174:177], v[26:29]
	v_mfma_i32_16x16x64_i8 v[22:25], v[158:161], v[182:185], v[22:25]
	v_mfma_i32_16x16x64_i8 v[18:21], v[166:169], v[182:185], v[18:21]
	v_mfma_i32_16x16x64_i8 v[14:17], v[158:161], v[190:193], v[14:17]
	v_mfma_i32_16x16x64_i8 v[10:13], v[166:169], v[190:193], v[10:13]
	v_mfma_i32_16x16x64_i8 v[6:9], v[158:161], v[198:201], v[6:9]
	v_mfma_i32_16x16x64_i8 v[2:5], v[166:169], v[198:201], v[2:5]
	s_setprio 0
	s_barrier
	ds_read_b128 v[132:135], v231
	ds_read_b128 v[136:139], v231 offset:1024
	ds_read_b128 v[146:149], v231 offset:2048
	ds_read_b128 v[150:153], v231 offset:3072
	ds_read_b128 v[154:157], v232
	ds_read_b128 v[158:161], v232 offset:1024
	ds_read_b128 v[162:165], v232 offset:2048
	ds_read_b128 v[166:169], v232 offset:3072
	s_mov_b32 m0, s59
	v_lshl_add_u64 v[206:207], v[204:205], 0, s[18:19]
	ds_read_b128 v[170:173], v219 offset:32768
	ds_read_b128 v[174:177], v219 offset:33792
	ds_read_b128 v[178:181], v219 offset:34816
	ds_read_b128 v[182:185], v219 offset:35840
	ds_read_b128 v[186:189], v219 offset:36864
	ds_read_b128 v[190:193], v219 offset:37888
	ds_read_b128 v[194:197], v219 offset:38912
	ds_read_b128 v[198:201], v219 offset:39936
	global_load_lds_dwordx4 v[206:207], off
	v_lshl_add_u64 v[206:207], v[204:205], 0, s[92:93]
	s_mov_b32 m0, s60
	s_nop 0
	global_load_lds_dwordx4 v[206:207], off
	s_waitcnt vmcnt(8)
	s_waitcnt lgkmcnt(0)
	s_barrier
	s_setprio 1
	s_waitcnt lgkmcnt(0)
	v_mfma_i32_16x16x64_i8 v[128:131], v[132:135], v[170:173], v[128:131]
	v_mfma_i32_16x16x64_i8 v[124:127], v[146:149], v[170:173], v[124:127]
	v_mfma_i32_16x16x64_i8 v[120:123], v[132:135], v[178:181], v[120:123]
	v_mfma_i32_16x16x64_i8 v[116:119], v[146:149], v[178:181], v[116:119]
	v_mfma_i32_16x16x64_i8 v[112:115], v[132:135], v[186:189], v[112:115]
	v_mfma_i32_16x16x64_i8 v[108:111], v[146:149], v[186:189], v[108:111]
	v_mfma_i32_16x16x64_i8 v[104:107], v[132:135], v[194:197], v[104:107]
	v_mfma_i32_16x16x64_i8 v[100:103], v[146:149], v[194:197], v[100:103]
	v_mfma_i32_16x16x64_i8 v[128:131], v[136:139], v[174:177], v[128:131]
	v_mfma_i32_16x16x64_i8 v[124:127], v[150:153], v[174:177], v[124:127]
	v_mfma_i32_16x16x64_i8 v[120:123], v[136:139], v[182:185], v[120:123]
	v_mfma_i32_16x16x64_i8 v[116:119], v[150:153], v[182:185], v[116:119]
	v_mfma_i32_16x16x64_i8 v[112:115], v[136:139], v[190:193], v[112:115]
	v_mfma_i32_16x16x64_i8 v[108:111], v[150:153], v[190:193], v[108:111]
	v_mfma_i32_16x16x64_i8 v[104:107], v[136:139], v[198:201], v[104:107]
	v_mfma_i32_16x16x64_i8 v[100:103], v[150:153], v[198:201], v[100:103]
	s_setprio 0
	s_setprio 1
	v_mfma_i32_16x16x64_i8 v[62:65], v[154:157], v[170:173], v[62:65]
	v_mfma_i32_16x16x64_i8 v[58:61], v[162:165], v[170:173], v[58:61]
	v_mfma_i32_16x16x64_i8 v[54:57], v[154:157], v[178:181], v[54:57]
	v_mfma_i32_16x16x64_i8 v[50:53], v[162:165], v[178:181], v[50:53]
	v_mfma_i32_16x16x64_i8 v[46:49], v[154:157], v[186:189], v[46:49]
	v_mfma_i32_16x16x64_i8 v[42:45], v[162:165], v[186:189], v[42:45]
	v_mfma_i32_16x16x64_i8 v[38:41], v[154:157], v[194:197], v[38:41]
	v_mfma_i32_16x16x64_i8 v[34:37], v[162:165], v[194:197], v[34:37]
	v_mfma_i32_16x16x64_i8 v[62:65], v[158:161], v[174:177], v[62:65]
	v_mfma_i32_16x16x64_i8 v[58:61], v[166:169], v[174:177], v[58:61]
	v_mfma_i32_16x16x64_i8 v[54:57], v[158:161], v[182:185], v[54:57]
	v_mfma_i32_16x16x64_i8 v[50:53], v[166:169], v[182:185], v[50:53]
	v_mfma_i32_16x16x64_i8 v[46:49], v[158:161], v[190:193], v[46:49]
	v_mfma_i32_16x16x64_i8 v[42:45], v[166:169], v[190:193], v[42:45]
	v_mfma_i32_16x16x64_i8 v[38:41], v[158:161], v[198:201], v[38:41]
	v_mfma_i32_16x16x64_i8 v[34:37], v[166:169], v[198:201], v[34:37]
	s_setprio 0
	s_barrier
; #define G_STAGE_B(bufoff, gbase) do { G_GLDS((const char*)(gbase) + voffB0, (bufoff) + ldsw); G_GLDS((const char*)(gbase) + vstep64 + voffB0, (bufoff) + ldsw + 8192); } while (0)
; #define G_STAGE_AU(bufoff, gbase) do { G_GLDS((const char*)(gbase) + voffA0, (bufoff) + ldsw); G_GLDS((const char*)(gbase) + vstep64 + voffA0, (bufoff) + ldsw + 8192); } while (0)
; #define X_LDA(b, h) do { if constexpr (MODE == 2) G_LDA8(A8, b, h); else G_LDA(At, b, h); } while (0)
; #define X_MMA0(ai, bj) do { if constexpr (MODE == 2) G_MMA8(ai, bj, A8, B08); else G_MMA(ai, bj, At, B0); } while (0)
; #define X_MMA1(ai, bj) do { if constexpr (MODE == 2) G_MMA8(ai, bj, A8, B18); else G_MMA(ai, bj, At, B1); } while (0)
; #define G_WAIT_V(n) asm volatile("s_waitcnt vmcnt(" #n ")" ::: "memory")
; #define G_WAIT_L(n) asm volatile("s_waitcnt lgkmcnt(" #n ")" ::: "memory")
; #define G_BAR __builtin_amdgcn_s_barrier()
; #define G_SCHED __builtin_amdgcn_sched_barrier(0)
;     ...
;             X_LDA(1, 1); G_STAGE_B(G_SB(1, 0), b3); G_STAGE_B(G_SB(1, 1), b3 + hstep); G_STAGE_AU(G_SA(1, 0), a3);
;             G_WAIT_V(8); G_WAIT_L(0); G_BAR; X_MMA0(1, 0); X_MMA1(1, 1); G_BAR; G_SCHED;
;         }
	s_mov_b32 m0, s61
	v_lshl_add_u64 v[206:207], v[202:203], 0, s[82:83]
	ds_read_b128 v[170:173], v219 offset:49152
	ds_read_b128 v[174:177], v219 offset:50176
	ds_read_b128 v[178:181], v219 offset:51200
	ds_read_b128 v[182:185], v219 offset:52224
	ds_read_b128 v[186:189], v219 offset:53248
	ds_read_b128 v[190:193], v219 offset:54272
	ds_read_b128 v[194:197], v219 offset:55296
	ds_read_b128 v[198:201], v219 offset:56320
	global_load_lds_dwordx4 v[206:207], off
	v_lshl_add_u64 v[206:207], v[202:203], 0, s[22:23]
	s_mov_b32 m0, s62
	s_nop 0
	global_load_lds_dwordx4 v[206:207], off
	v_lshl_add_u64 v[206:207], v[202:203], 0, s[88:89]
	s_mov_b32 m0, s65
	v_lshl_add_u64 v[202:203], v[202:203], 0, s[74:75]
	global_load_lds_dwordx4 v[206:207], off
	s_mov_b32 m0, s66
	s_nop 0
	global_load_lds_dwordx4 v[202:203], off
	v_lshl_add_u64 v[202:203], v[204:205], 0, s[82:83]
	s_mov_b32 m0, s63
	s_nop 0
	global_load_lds_dwordx4 v[202:203], off
	v_lshl_add_u64 v[202:203], v[204:205], 0, s[22:23]
	s_mov_b32 m0, s64
	s_nop 0
	global_load_lds_dwordx4 v[202:203], off
	s_waitcnt vmcnt(8)
	s_waitcnt lgkmcnt(0)
	s_barrier
	s_setprio 1
	s_waitcnt lgkmcnt(0)
	v_mfma_i32_16x16x64_i8 v[96:99], v[132:135], v[170:173], v[96:99]
	v_mfma_i32_16x16x64_i8 v[92:95], v[146:149], v[170:173], v[92:95]
	v_mfma_i32_16x16x64_i8 v[88:91], v[132:135], v[178:181], v[88:91]
	v_mfma_i32_16x16x64_i8 v[84:87], v[146:149], v[178:181], v[84:87]
	v_mfma_i32_16x16x64_i8 v[80:83], v[132:135], v[186:189], v[80:83]
	v_mfma_i32_16x16x64_i8 v[76:79], v[146:149], v[186:189], v[76:79]
	v_mfma_i32_16x16x64_i8 v[72:75], v[132:135], v[194:197], v[72:75]
	v_mfma_i32_16x16x64_i8 v[68:71], v[146:149], v[194:197], v[68:71]
	v_mfma_i32_16x16x64_i8 v[96:99], v[136:139], v[174:177], v[96:99]
	v_mfma_i32_16x16x64_i8 v[92:95], v[150:153], v[174:177], v[92:95]
	v_mfma_i32_16x16x64_i8 v[88:91], v[136:139], v[182:185], v[88:91]
	v_mfma_i32_16x16x64_i8 v[84:87], v[150:153], v[182:185], v[84:87]
	v_mfma_i32_16x16x64_i8 v[80:83], v[136:139], v[190:193], v[80:83]
	v_mfma_i32_16x16x64_i8 v[76:79], v[150:153], v[190:193], v[76:79]
	v_mfma_i32_16x16x64_i8 v[72:75], v[136:139], v[198:201], v[72:75]
	v_mfma_i32_16x16x64_i8 v[68:71], v[150:153], v[198:201], v[68:71]
	s_setprio 0
	s_setprio 1
	v_mfma_i32_16x16x64_i8 v[30:33], v[154:157], v[170:173], v[30:33]
	v_mfma_i32_16x16x64_i8 v[26:29], v[162:165], v[170:173], v[26:29]
	v_mfma_i32_16x16x64_i8 v[22:25], v[154:157], v[178:181], v[22:25]
	v_mfma_i32_16x16x64_i8 v[18:21], v[162:165], v[178:181], v[18:21]
	v_mfma_i32_16x16x64_i8 v[14:17], v[154:157], v[186:189], v[14:17]
	v_mfma_i32_16x16x64_i8 v[10:13], v[162:165], v[186:189], v[10:13]
	v_mfma_i32_16x16x64_i8 v[6:9], v[154:157], v[194:197], v[6:9]
	v_mfma_i32_16x16x64_i8 v[2:5], v[162:165], v[194:197], v[2:5]
	v_mfma_i32_16x16x64_i8 v[30:33], v[158:161], v[174:177], v[30:33]
	v_mfma_i32_16x16x64_i8 v[26:29], v[166:169], v[174:177], v[26:29]
	v_mfma_i32_16x16x64_i8 v[22:25], v[158:161], v[182:185], v[22:25]
	v_mfma_i32_16x16x64_i8 v[18:21], v[166:169], v[182:185], v[18:21]
	v_mfma_i32_16x16x64_i8 v[14:17], v[158:161], v[190:193], v[14:17]
	v_mfma_i32_16x16x64_i8 v[10:13], v[166:169], v[190:193], v[10:13]
	v_mfma_i32_16x16x64_i8 v[6:9], v[158:161], v[198:201], v[6:9]
	v_mfma_i32_16x16x64_i8 v[2:5], v[166:169], v[198:201], v[2:5]
	s_setprio 0
	s_barrier
	s_add_i32 s11, s11, 2
	s_add_u32 s0, s0, 0x100
	s_addc_u32 s1, s1, 0
	s_add_u32 s8, s8, 0x100
	s_addc_u32 s9, s9, 0
	s_cmp_gt_u32 s11, 5
	s_cbranch_scc0 .LBB0_203
